# P6 epilogue: last read of x_prompt non-temporal (nt)
# baseline (speedup 1.0000x reference)
; #define LAUNDER_GPTR(p) do { p = launder_gptr(p); } while (0)
;     __device__ __forceinline__ void operator()(const f32x4 (&acc)[2][2][4][2], const Unit& u, int wr, int wc, int fr, int fq) const {
;         unsigned char* ws = P->ws; LAUNDER_GPTR(ws);
;         const float* MOD = (const float*)(ws + WS_MOD);
;         float* X1 = (float*)(ws + WS_X1);
;         const int col0 = u.pn * 256 + wc * 32 + 8 * fq;
; #pragma unroll
;         for (int ai = 0; ai < 2; ++ai)
; #pragma unroll
;             for (int m = 0; m < 4; ++m) {
;                 const int r = u.pm * 256 + ai * 128 + wr * 64 + m * 16 + fr;
;                 const float* gate = MOD + (size_t)mod_row(r) * 6144 + (WHICH == 0 ? 2048 : 5120) + col0;
;                 const float* res = (WHICH == 0) ? (r < NPR ? P->in[0] + (size_t)r * DM : P->in[1] + (size_t)(r - NPR) * DM) + col0 : X1 + (size_t)r * DM + col0;
;                 float* dst = (WHICH == 0) ? X1 + (size_t)r * DM + col0 : P->out + (size_t)r * DM + col0;
; #pragma unroll
;                 for (int bj = 0; bj < 2; ++bj)
; #pragma unroll
;                     for (int n = 0; n < 2; ++n) { const int o = bj * 128 + 4 * n;
;                         const f32x4 g = *(const f32x4*)(gate + o), x = *(const f32x4*)(res + o);
;                         *(f32x4*)(dst + o) = x + g * acc[ai][bj][m][n]; }
;             }
;     }
.LBB0_1679:
	s_lshl_b32 s27, s6, 8
	s_add_i32 s27, s27, s52
	v_or_b32_e32 v150, s27, v154
	s_mov_b64 s[38:39], s[14:15]
	v_cmp_gt_i32_e32 vcc, s50, v150
	v_cmp_lt_i32_e64 s[6:7], s59, v150
	v_add_u32_e32 v136, 0xffffc000, v150
	s_and_saveexec_b64 s[40:41], s[6:7]
	s_xor_b64 s[6:7], exec, s[40:41]
	v_lshlrev_b64 v[146:147], 12, v[136:137]
	v_mov_b32_e32 v151, v137
	v_lshl_add_u64 v[148:149], s[10:11], 0, v[146:147]
	v_lshlrev_b64 v[152:153], 12, v[150:151]
	s_andn2_saveexec_b64 s[6:7], s[6:7]
	v_ashrrev_i32_e32 v151, 31, v150
	v_lshlrev_b64 v[152:153], 12, v[150:151]
	v_lshl_add_u64 v[148:149], s[8:9], 0, v[152:153]
	s_or_b64 exec, exec, s[6:7]
	s_ashr_i32 s29, s27, 13
	v_lshrrev_b32_e32 v136, 2, v136
	v_lshl_or_b32 v146, s36, 8, v156
	v_add_u32_e32 v136, 2, v136
	v_mov_b32_e32 v151, s29
	v_ashrrev_i32_e32 v147, 31, v146
	v_cndmask_b32_e32 v136, v136, v151, vcc
	v_mov_b64_e32 v[160:161], s[38:39]
	v_lshlrev_b64 v[146:147], 2, v[146:147]
	v_mad_i64_i32 v[160:161], s[6:7], v136, s51, v[160:161]
	v_lshl_add_u64 v[168:169], v[160:161], 0, v[146:147]
	v_lshl_add_u64 v[170:171], v[148:149], 0, v[146:147]
	v_add_co_u32_e32 v148, vcc, s60, v168
	v_add_u32_e32 v136, 0xffffc010, v150
	s_nop 0
	v_addc_co_u32_e32 v149, vcc, 0, v169, vcc
	global_load_dwordx4 v[160:163], v[170:171], off nt
	global_load_dwordx4 v[164:167], v[148:149], off
	v_lshl_add_u64 v[148:149], s[38:39], 0, v[146:147]
	v_lshl_add_u64 v[148:149], v[148:149], 0, s[22:23]
	v_lshl_add_u64 v[152:153], v[148:149], 0, v[152:153]
	v_lshl_add_u64 v[168:169], v[168:169], 0, s[24:25]
	s_waitcnt vmcnt(0)
	v_pk_fma_f32 v[126:127], v[126:127], v[166:167], v[162:163]
	v_pk_fma_f32 v[124:125], v[124:125], v[164:165], v[160:161]
	global_store_dwordx4 v[152:153], v[124:127], off
	global_load_dwordx4 v[124:127], v[168:169], off offset:16
	s_nop 0
	global_load_dwordx4 v[160:163], v[170:171], off offset:16 nt
	s_waitcnt vmcnt(0)
	v_pk_fma_f32 v[122:123], v[122:123], v[126:127], v[162:163]
	v_pk_fma_f32 v[120:121], v[120:121], v[124:125], v[160:161]
	global_store_dwordx4 v[152:153], v[120:123], off offset:16
	global_load_dwordx4 v[120:123], v[168:169], off offset:512
	s_nop 0
	global_load_dwordx4 v[124:127], v[170:171], off offset:512 nt
	s_waitcnt vmcnt(0)
	v_pk_fma_f32 v[118:119], v[118:119], v[122:123], v[126:127]
	v_pk_fma_f32 v[116:117], v[116:117], v[120:121], v[124:125]
	global_store_dwordx4 v[152:153], v[116:119], off offset:512
	global_load_dwordx4 v[118:121], v[168:169], off offset:528
	s_nop 0
	global_load_dwordx4 v[122:125], v[170:171], off offset:528 nt
	v_or_b32_e32 v116, 16, v150
	v_cmp_gt_i32_e32 vcc, s50, v116
	v_cmp_lt_i32_e64 s[6:7], s59, v116
	s_waitcnt vmcnt(0)
	v_pk_fma_f32 v[114:115], v[114:115], v[120:121], v[124:125]
	v_pk_fma_f32 v[112:113], v[112:113], v[118:119], v[122:123]
	global_store_dwordx4 v[152:153], v[112:115], off offset:528
	s_and_saveexec_b64 s[40:41], s[6:7]
	s_xor_b64 s[6:7], exec, s[40:41]
	v_lshlrev_b64 v[112:113], 12, v[136:137]
	v_mov_b32_e32 v117, v137
	v_lshl_add_u64 v[114:115], s[10:11], 0, v[112:113]
	v_lshlrev_b64 v[112:113], 12, v[116:117]
	s_andn2_saveexec_b64 s[6:7], s[6:7]
	v_ashrrev_i32_e32 v117, 31, v116
	v_lshlrev_b64 v[112:113], 12, v[116:117]
	v_lshl_add_u64 v[114:115], s[8:9], 0, v[112:113]
	s_or_b64 exec, exec, s[6:7]
	v_lshrrev_b32_e32 v116, 2, v136
	v_add_u32_e32 v116, 2, v116
	v_mov_b32_e32 v117, s29
	v_cndmask_b32_e32 v118, v116, v117, vcc
	v_mov_b64_e32 v[116:117], s[38:39]
	v_mad_i64_i32 v[116:117], s[6:7], v118, s51, v[116:117]
	v_lshl_add_u64 v[122:123], v[116:117], 0, v[146:147]
	v_add_co_u32_e32 v118, vcc, 0x2102000, v122
	v_lshl_add_u64 v[124:125], v[114:115], 0, v[146:147]
	s_nop 0
	v_addc_co_u32_e32 v119, vcc, 0, v123, vcc
	global_load_dwordx4 v[114:117], v[124:125], off nt
	s_nop 0
	global_load_dwordx4 v[118:121], v[118:119], off
	v_lshl_add_u64 v[126:127], v[148:149], 0, v[112:113]
	v_lshl_add_u64 v[122:123], v[122:123], 0, s[24:25]
	v_add_u32_e32 v136, 0xffffc020, v150
	s_waitcnt vmcnt(0)
	v_pk_fma_f32 v[110:111], v[110:111], v[120:121], v[116:117]
	v_pk_fma_f32 v[108:109], v[108:109], v[118:119], v[114:115]
	global_store_dwordx4 v[126:127], v[108:111], off
	global_load_dwordx4 v[108:111], v[122:123], off offset:16
	s_nop 0
	global_load_dwordx4 v[112:115], v[124:125], off offset:16 nt
	s_waitcnt vmcnt(0)
	v_pk_fma_f32 v[106:107], v[106:107], v[110:111], v[114:115]
	v_pk_fma_f32 v[104:105], v[104:105], v[108:109], v[112:113]
	global_store_dwordx4 v[126:127], v[104:107], off offset:16
	global_load_dwordx4 v[104:107], v[122:123], off offset:512
	s_nop 0
	global_load_dwordx4 v[108:111], v[124:125], off offset:512 nt
	s_waitcnt vmcnt(0)
	v_pk_fma_f32 v[102:103], v[102:103], v[106:107], v[110:111]
	v_pk_fma_f32 v[100:101], v[100:101], v[104:105], v[108:109]
	global_store_dwordx4 v[126:127], v[100:103], off offset:512
	global_load_dwordx4 v[102:105], v[122:123], off offset:528
	s_nop 0
	global_load_dwordx4 v[106:109], v[124:125], off offset:528 nt
	v_or_b32_e32 v100, 32, v150
	v_cmp_gt_i32_e32 vcc, s50, v100
	v_cmp_lt_i32_e64 s[6:7], s59, v100
	s_waitcnt vmcnt(0)
; #define LAUNDER_GPTR(p) do { p = launder_gptr(p); } while (0)
;     __device__ __forceinline__ void operator()(const f32x4 (&acc)[2][2][4][2], const Unit& u, int wr, int wc, int fr, int fq) const {
;         unsigned char* ws = P->ws; LAUNDER_GPTR(ws);
;         const float* MOD = (const float*)(ws + WS_MOD);
;         float* X1 = (float*)(ws + WS_X1);
;         const int col0 = u.pn * 256 + wc * 32 + 8 * fq;
; #pragma unroll
;         for (int ai = 0; ai < 2; ++ai)
; #pragma unroll
;             for (int m = 0; m < 4; ++m) {
;                 const int r = u.pm * 256 + ai * 128 + wr * 64 + m * 16 + fr;
;                 const float* gate = MOD + (size_t)mod_row(r) * 6144 + (WHICH == 0 ? 2048 : 5120) + col0;
;                 const float* res = (WHICH == 0) ? (r < NPR ? P->in[0] + (size_t)r * DM : P->in[1] + (size_t)(r - NPR) * DM) + col0 : X1 + (size_t)r * DM + col0;
;                 float* dst = (WHICH == 0) ? X1 + (size_t)r * DM + col0 : P->out + (size_t)r * DM + col0;
; #pragma unroll
;                 for (int bj = 0; bj < 2; ++bj)
; #pragma unroll
;                     for (int n = 0; n < 2; ++n) { const int o = bj * 128 + 4 * n;
;                         const f32x4 g = *(const f32x4*)(gate + o), x = *(const f32x4*)(res + o);
;                         *(f32x4*)(dst + o) = x + g * acc[ai][bj][m][n]; }
;             }
;     }
	v_pk_fma_f32 v[98:99], v[98:99], v[104:105], v[108:109]
	v_pk_fma_f32 v[96:97], v[96:97], v[102:103], v[106:107]
	global_store_dwordx4 v[126:127], v[96:99], off offset:528
	s_and_saveexec_b64 s[40:41], s[6:7]
	s_xor_b64 s[6:7], exec, s[40:41]
	v_lshlrev_b64 v[96:97], 12, v[136:137]
	v_mov_b32_e32 v101, v137
	v_lshl_add_u64 v[98:99], s[10:11], 0, v[96:97]
	v_lshlrev_b64 v[96:97], 12, v[100:101]
	s_andn2_saveexec_b64 s[6:7], s[6:7]
	v_ashrrev_i32_e32 v101, 31, v100
	v_lshlrev_b64 v[96:97], 12, v[100:101]
	v_lshl_add_u64 v[98:99], s[8:9], 0, v[96:97]
	s_or_b64 exec, exec, s[6:7]
	v_lshrrev_b32_e32 v100, 2, v136
	v_add_u32_e32 v100, 2, v100
	v_mov_b32_e32 v101, s29
	v_cndmask_b32_e32 v102, v100, v101, vcc
	v_mov_b64_e32 v[100:101], s[38:39]
	v_mad_i64_i32 v[100:101], s[6:7], v102, s51, v[100:101]
	v_lshl_add_u64 v[106:107], v[100:101], 0, v[146:147]
	v_add_co_u32_e32 v102, vcc, 0x2102000, v106
	v_lshl_add_u64 v[108:109], v[98:99], 0, v[146:147]
	s_nop 0
	v_addc_co_u32_e32 v103, vcc, 0, v107, vcc
	global_load_dwordx4 v[98:101], v[108:109], off nt
	s_nop 0
	global_load_dwordx4 v[102:105], v[102:103], off
	v_lshl_add_u64 v[110:111], v[148:149], 0, v[96:97]
	v_lshl_add_u64 v[106:107], v[106:107], 0, s[24:25]
	v_add_u32_e32 v136, 0xffffc030, v150
	s_waitcnt vmcnt(0)
	v_pk_fma_f32 v[94:95], v[94:95], v[104:105], v[100:101]
	v_pk_fma_f32 v[92:93], v[92:93], v[102:103], v[98:99]
	global_store_dwordx4 v[110:111], v[92:95], off
	global_load_dwordx4 v[92:95], v[106:107], off offset:16
	s_nop 0
	global_load_dwordx4 v[96:99], v[108:109], off offset:16 nt
	s_waitcnt vmcnt(0)
	v_pk_fma_f32 v[90:91], v[90:91], v[94:95], v[98:99]
	v_pk_fma_f32 v[88:89], v[88:89], v[92:93], v[96:97]
	global_store_dwordx4 v[110:111], v[88:91], off offset:16
	global_load_dwordx4 v[88:91], v[106:107], off offset:512
	s_nop 0
	global_load_dwordx4 v[92:95], v[108:109], off offset:512 nt
	s_waitcnt vmcnt(0)
	v_pk_fma_f32 v[86:87], v[86:87], v[90:91], v[94:95]
	v_pk_fma_f32 v[84:85], v[84:85], v[88:89], v[92:93]
	global_store_dwordx4 v[110:111], v[84:87], off offset:512
	global_load_dwordx4 v[86:89], v[106:107], off offset:528
	s_nop 0
	global_load_dwordx4 v[90:93], v[108:109], off offset:528 nt
	v_or_b32_e32 v84, 48, v150
	v_cmp_gt_i32_e32 vcc, s50, v84
	v_cmp_lt_i32_e64 s[6:7], s59, v84
	s_waitcnt vmcnt(0)
	v_pk_fma_f32 v[82:83], v[82:83], v[88:89], v[92:93]
	v_pk_fma_f32 v[80:81], v[80:81], v[86:87], v[90:91]
	global_store_dwordx4 v[110:111], v[80:83], off offset:528
	s_and_saveexec_b64 s[40:41], s[6:7]
	s_xor_b64 s[6:7], exec, s[40:41]
	v_lshlrev_b64 v[80:81], 12, v[136:137]
	v_mov_b32_e32 v85, v137
	v_lshl_add_u64 v[82:83], s[10:11], 0, v[80:81]
	v_lshlrev_b64 v[80:81], 12, v[84:85]
	s_andn2_saveexec_b64 s[6:7], s[6:7]
	v_ashrrev_i32_e32 v85, 31, v84
	v_lshlrev_b64 v[80:81], 12, v[84:85]
	v_lshl_add_u64 v[82:83], s[8:9], 0, v[80:81]
	s_or_b64 exec, exec, s[6:7]
	v_lshrrev_b32_e32 v84, 2, v136
	v_add_u32_e32 v84, 2, v84
	v_mov_b32_e32 v85, s29
	v_cndmask_b32_e32 v86, v84, v85, vcc
	v_mov_b64_e32 v[84:85], s[38:39]
	v_mad_i64_i32 v[84:85], s[6:7], v86, s51, v[84:85]
	v_lshl_add_u64 v[90:91], v[84:85], 0, v[146:147]
	v_add_co_u32_e32 v86, vcc, 0x2102000, v90
	v_lshl_add_u64 v[92:93], v[82:83], 0, v[146:147]
	s_nop 0
	v_addc_co_u32_e32 v87, vcc, 0, v91, vcc
	global_load_dwordx4 v[82:85], v[92:93], off nt
	s_nop 0
	global_load_dwordx4 v[86:89], v[86:87], off
	v_lshl_add_u64 v[94:95], v[148:149], 0, v[80:81]
	v_lshl_add_u64 v[90:91], v[90:91], 0, s[24:25]
	s_addk_i32 s27, 0x80
	s_waitcnt vmcnt(0)
	v_pk_fma_f32 v[78:79], v[78:79], v[88:89], v[84:85]
	v_pk_fma_f32 v[76:77], v[76:77], v[86:87], v[82:83]
	global_store_dwordx4 v[94:95], v[76:79], off
	global_load_dwordx4 v[76:79], v[90:91], off offset:16
	s_nop 0
	global_load_dwordx4 v[80:83], v[92:93], off offset:16 nt
	s_waitcnt vmcnt(0)
	v_pk_fma_f32 v[74:75], v[74:75], v[78:79], v[82:83]
	v_pk_fma_f32 v[72:73], v[72:73], v[76:77], v[80:81]
	global_store_dwordx4 v[94:95], v[72:75], off offset:16
	global_load_dwordx4 v[72:75], v[90:91], off offset:512
	s_nop 0
	global_load_dwordx4 v[76:79], v[92:93], off offset:512 nt
	s_waitcnt vmcnt(0)
	v_pk_fma_f32 v[70:71], v[70:71], v[74:75], v[78:79]
	v_pk_fma_f32 v[68:69], v[68:69], v[72:73], v[76:77]
	global_store_dwordx4 v[94:95], v[68:71], off offset:512
	global_load_dwordx4 v[70:73], v[90:91], off offset:528
	s_nop 0
	global_load_dwordx4 v[74:77], v[92:93], off offset:528 nt
	v_or_b32_e32 v68, s27, v154
	v_cmp_gt_i32_e32 vcc, s50, v68
	v_cmp_lt_i32_e64 s[6:7], s59, v68
	v_add_u32_e32 v136, 0xffffc000, v68
	s_waitcnt vmcnt(0)
	v_pk_fma_f32 v[66:67], v[66:67], v[72:73], v[76:77]
	v_pk_fma_f32 v[64:65], v[64:65], v[70:71], v[74:75]
	global_store_dwordx4 v[94:95], v[64:67], off offset:528
	s_and_saveexec_b64 s[40:41], s[6:7]
	s_xor_b64 s[6:7], exec, s[40:41]
	v_lshlrev_b64 v[64:65], 12, v[136:137]
	v_mov_b32_e32 v69, v137
	v_lshl_add_u64 v[66:67], s[10:11], 0, v[64:65]
	v_lshlrev_b64 v[64:65], 12, v[68:69]
	s_andn2_saveexec_b64 s[6:7], s[6:7]
	v_ashrrev_i32_e32 v69, 31, v68
	v_lshlrev_b64 v[64:65], 12, v[68:69]
	v_lshl_add_u64 v[66:67], s[8:9], 0, v[64:65]
	s_or_b64 exec, exec, s[6:7]
	s_ashr_i32 s27, s27, 13
	v_lshrrev_b32_e32 v69, 2, v136
	v_add_u32_e32 v69, 2, v69
	v_mov_b32_e32 v70, s27
	v_cndmask_b32_e32 v69, v69, v70, vcc
	v_mov_b64_e32 v[70:71], s[38:39]
	v_mad_i64_i32 v[70:71], s[6:7], v69, s51, v[70:71]
	v_lshl_add_u64 v[78:79], v[70:71], 0, v[146:147]
	v_lshl_add_u64 v[80:81], v[66:67], 0, v[146:147]
	v_add_co_u32_e32 v66, vcc, 0x2102000, v78
	v_lshl_add_u64 v[82:83], v[148:149], 0, v[64:65]
	s_nop 0
	v_addc_co_u32_e32 v67, vcc, 0, v79, vcc
	global_load_dwordx4 v[70:73], v[80:81], off nt
	global_load_dwordx4 v[74:77], v[66:67], off
	v_lshl_add_u64 v[78:79], v[78:79], 0, s[24:25]
	v_add_u32_e32 v136, 0xffffc010, v68
	s_waitcnt vmcnt(0)
; #define LAUNDER_GPTR(p) do { p = launder_gptr(p); } while (0)
;     __device__ __forceinline__ void operator()(const f32x4 (&acc)[2][2][4][2], const Unit& u, int wr, int wc, int fr, int fq) const {
;         unsigned char* ws = P->ws; LAUNDER_GPTR(ws);
;         const float* MOD = (const float*)(ws + WS_MOD);
;         float* X1 = (float*)(ws + WS_X1);
;         const int col0 = u.pn * 256 + wc * 32 + 8 * fq;
; #pragma unroll
;         for (int ai = 0; ai < 2; ++ai)
; #pragma unroll
;             for (int m = 0; m < 4; ++m) {
;                 const int r = u.pm * 256 + ai * 128 + wr * 64 + m * 16 + fr;
;                 const float* gate = MOD + (size_t)mod_row(r) * 6144 + (WHICH == 0 ? 2048 : 5120) + col0;
;                 const float* res = (WHICH == 0) ? (r < NPR ? P->in[0] + (size_t)r * DM : P->in[1] + (size_t)(r - NPR) * DM) + col0 : X1 + (size_t)r * DM + col0;
;                 float* dst = (WHICH == 0) ? X1 + (size_t)r * DM + col0 : P->out + (size_t)r * DM + col0;
; #pragma unroll
;                 for (int bj = 0; bj < 2; ++bj)
; #pragma unroll
;                     for (int n = 0; n < 2; ++n) { const int o = bj * 128 + 4 * n;
;                         const f32x4 g = *(const f32x4*)(gate + o), x = *(const f32x4*)(res + o);
;                         *(f32x4*)(dst + o) = x + g * acc[ai][bj][m][n]; }
;             }
;     }
	v_pk_fma_f32 v[62:63], v[62:63], v[76:77], v[72:73]
	v_pk_fma_f32 v[60:61], v[60:61], v[74:75], v[70:71]
	global_store_dwordx4 v[82:83], v[60:63], off
	global_load_dwordx4 v[60:63], v[78:79], off offset:16
	s_nop 0
	global_load_dwordx4 v[64:67], v[80:81], off offset:16 nt
	s_waitcnt vmcnt(0)
	v_pk_fma_f32 v[58:59], v[58:59], v[62:63], v[66:67]
	v_pk_fma_f32 v[56:57], v[56:57], v[60:61], v[64:65]
	global_store_dwordx4 v[82:83], v[56:59], off offset:16
	global_load_dwordx4 v[56:59], v[78:79], off offset:512
	s_nop 0
	global_load_dwordx4 v[60:63], v[80:81], off offset:512 nt
	s_waitcnt vmcnt(0)
	v_pk_fma_f32 v[54:55], v[54:55], v[58:59], v[62:63]
	v_pk_fma_f32 v[52:53], v[52:53], v[56:57], v[60:61]
	global_store_dwordx4 v[82:83], v[52:55], off offset:512
	global_load_dwordx4 v[54:57], v[78:79], off offset:528
	s_nop 0
	global_load_dwordx4 v[58:61], v[80:81], off offset:528 nt
	v_or_b32_e32 v52, 16, v68
	v_cmp_gt_i32_e32 vcc, s50, v52
	v_cmp_lt_i32_e64 s[6:7], s59, v52
	s_waitcnt vmcnt(0)
	v_pk_fma_f32 v[50:51], v[50:51], v[56:57], v[60:61]
	v_pk_fma_f32 v[48:49], v[48:49], v[54:55], v[58:59]
	global_store_dwordx4 v[82:83], v[48:51], off offset:528
	s_and_saveexec_b64 s[40:41], s[6:7]
	s_xor_b64 s[6:7], exec, s[40:41]
	v_lshlrev_b64 v[48:49], 12, v[136:137]
	v_mov_b32_e32 v53, v137
	v_lshl_add_u64 v[50:51], s[10:11], 0, v[48:49]
	v_lshlrev_b64 v[48:49], 12, v[52:53]
	s_andn2_saveexec_b64 s[6:7], s[6:7]
	v_ashrrev_i32_e32 v53, 31, v52
	v_lshlrev_b64 v[48:49], 12, v[52:53]
	v_lshl_add_u64 v[50:51], s[8:9], 0, v[48:49]
	s_or_b64 exec, exec, s[6:7]
	v_lshrrev_b32_e32 v52, 2, v136
	v_add_u32_e32 v52, 2, v52
	v_mov_b32_e32 v53, s27
	v_cndmask_b32_e32 v54, v52, v53, vcc
	v_mov_b64_e32 v[52:53], s[38:39]
	v_mad_i64_i32 v[52:53], s[6:7], v54, s51, v[52:53]
	v_lshl_add_u64 v[58:59], v[52:53], 0, v[146:147]
	v_add_co_u32_e32 v54, vcc, 0x2102000, v58
	v_lshl_add_u64 v[60:61], v[50:51], 0, v[146:147]
	s_nop 0
	v_addc_co_u32_e32 v55, vcc, 0, v59, vcc
	global_load_dwordx4 v[50:53], v[60:61], off nt
	s_nop 0
	global_load_dwordx4 v[54:57], v[54:55], off
	v_lshl_add_u64 v[62:63], v[148:149], 0, v[48:49]
	v_lshl_add_u64 v[58:59], v[58:59], 0, s[24:25]
	v_add_u32_e32 v136, 0xffffc020, v68
	s_waitcnt vmcnt(0)
	v_pk_fma_f32 v[46:47], v[46:47], v[56:57], v[52:53]
	v_pk_fma_f32 v[44:45], v[44:45], v[54:55], v[50:51]
	global_store_dwordx4 v[62:63], v[44:47], off
	global_load_dwordx4 v[44:47], v[58:59], off offset:16
	s_nop 0
	global_load_dwordx4 v[48:51], v[60:61], off offset:16 nt
	s_waitcnt vmcnt(0)
	v_pk_fma_f32 v[42:43], v[42:43], v[46:47], v[50:51]
	v_pk_fma_f32 v[40:41], v[40:41], v[44:45], v[48:49]
	global_store_dwordx4 v[62:63], v[40:43], off offset:16
	global_load_dwordx4 v[40:43], v[58:59], off offset:512
	s_nop 0
	global_load_dwordx4 v[44:47], v[60:61], off offset:512 nt
	s_waitcnt vmcnt(0)
	v_pk_fma_f32 v[38:39], v[38:39], v[42:43], v[46:47]
	v_pk_fma_f32 v[36:37], v[36:37], v[40:41], v[44:45]
	global_store_dwordx4 v[62:63], v[36:39], off offset:512
	global_load_dwordx4 v[38:41], v[58:59], off offset:528
	s_nop 0
	global_load_dwordx4 v[42:45], v[60:61], off offset:528 nt
	v_or_b32_e32 v36, 32, v68
	v_cmp_gt_i32_e32 vcc, s50, v36
	v_cmp_lt_i32_e64 s[6:7], s59, v36
	s_waitcnt vmcnt(0)
	v_pk_fma_f32 v[34:35], v[34:35], v[40:41], v[44:45]
	v_pk_fma_f32 v[32:33], v[32:33], v[38:39], v[42:43]
	global_store_dwordx4 v[62:63], v[32:35], off offset:528
	s_and_saveexec_b64 s[40:41], s[6:7]
	s_xor_b64 s[6:7], exec, s[40:41]
	v_lshlrev_b64 v[32:33], 12, v[136:137]
	v_mov_b32_e32 v37, v137
	v_lshl_add_u64 v[34:35], s[10:11], 0, v[32:33]
	v_lshlrev_b64 v[32:33], 12, v[36:37]
	s_andn2_saveexec_b64 s[6:7], s[6:7]
	v_ashrrev_i32_e32 v37, 31, v36
	v_lshlrev_b64 v[32:33], 12, v[36:37]
	v_lshl_add_u64 v[34:35], s[8:9], 0, v[32:33]
	s_or_b64 exec, exec, s[6:7]
	v_lshrrev_b32_e32 v36, 2, v136
	v_add_u32_e32 v36, 2, v36
	v_mov_b32_e32 v37, s27
	v_cndmask_b32_e32 v38, v36, v37, vcc
	v_mov_b64_e32 v[36:37], s[38:39]
	v_mad_i64_i32 v[36:37], s[6:7], v38, s51, v[36:37]
	v_lshl_add_u64 v[42:43], v[36:37], 0, v[146:147]
	v_add_co_u32_e32 v38, vcc, 0x2102000, v42
	v_lshl_add_u64 v[44:45], v[34:35], 0, v[146:147]
	s_nop 0
	v_addc_co_u32_e32 v39, vcc, 0, v43, vcc
	global_load_dwordx4 v[34:37], v[44:45], off nt
	s_nop 0
	global_load_dwordx4 v[38:41], v[38:39], off
	v_lshl_add_u64 v[46:47], v[148:149], 0, v[32:33]
	v_lshl_add_u64 v[42:43], v[42:43], 0, s[24:25]
	s_waitcnt vmcnt(0)
; #define LAUNDER_GPTR(p) do { p = launder_gptr(p); } while (0)
;     __device__ __forceinline__ void operator()(const f32x4 (&acc)[2][2][4][2], const Unit& u, int wr, int wc, int fr, int fq) const {
;         unsigned char* ws = P->ws; LAUNDER_GPTR(ws);
;         const float* MOD = (const float*)(ws + WS_MOD);
;         float* X1 = (float*)(ws + WS_X1);
;         const int col0 = u.pn * 256 + wc * 32 + 8 * fq;
; #pragma unroll
;         for (int ai = 0; ai < 2; ++ai)
; #pragma unroll
;             for (int m = 0; m < 4; ++m) {
;                 const int r = u.pm * 256 + ai * 128 + wr * 64 + m * 16 + fr;
;                 const float* gate = MOD + (size_t)mod_row(r) * 6144 + (WHICH == 0 ? 2048 : 5120) + col0;
;                 const float* res = (WHICH == 0) ? (r < NPR ? P->in[0] + (size_t)r * DM : P->in[1] + (size_t)(r - NPR) * DM) + col0 : X1 + (size_t)r * DM + col0;
;                 float* dst = (WHICH == 0) ? X1 + (size_t)r * DM + col0 : P->out + (size_t)r * DM + col0;
; #pragma unroll
;                 for (int bj = 0; bj < 2; ++bj)
; #pragma unroll
;                     for (int n = 0; n < 2; ++n) { const int o = bj * 128 + 4 * n;
;                         const f32x4 g = *(const f32x4*)(gate + o), x = *(const f32x4*)(res + o);
;                         *(f32x4*)(dst + o) = x + g * acc[ai][bj][m][n]; }
;             }
;     }
	v_pk_fma_f32 v[30:31], v[30:31], v[40:41], v[36:37]
	v_pk_fma_f32 v[28:29], v[28:29], v[38:39], v[34:35]
	global_store_dwordx4 v[46:47], v[28:31], off
	global_load_dwordx4 v[28:31], v[42:43], off offset:16
	s_nop 0
	global_load_dwordx4 v[32:35], v[44:45], off offset:16 nt
	s_waitcnt vmcnt(0)
	v_pk_fma_f32 v[26:27], v[26:27], v[30:31], v[34:35]
	v_pk_fma_f32 v[24:25], v[24:25], v[28:29], v[32:33]
	global_store_dwordx4 v[46:47], v[24:27], off offset:16
	global_load_dwordx4 v[24:27], v[42:43], off offset:512
	s_nop 0
	global_load_dwordx4 v[28:31], v[44:45], off offset:512 nt
	s_waitcnt vmcnt(0)
	v_pk_fma_f32 v[22:23], v[22:23], v[26:27], v[30:31]
	v_pk_fma_f32 v[20:21], v[20:21], v[24:25], v[28:29]
	global_store_dwordx4 v[46:47], v[20:23], off offset:512
	global_load_dwordx4 v[22:25], v[42:43], off offset:528
	s_nop 0
	global_load_dwordx4 v[26:29], v[44:45], off offset:528 nt
	v_or_b32_e32 v20, 48, v68
	v_cmp_lt_i32_e32 vcc, s59, v20
	s_waitcnt vmcnt(0)
	v_pk_fma_f32 v[18:19], v[18:19], v[24:25], v[28:29]
	v_pk_fma_f32 v[16:17], v[16:17], v[22:23], v[26:27]
	global_store_dwordx4 v[46:47], v[16:19], off offset:528
	s_and_saveexec_b64 s[6:7], vcc
	s_xor_b64 s[6:7], exec, s[6:7]
	v_add_u32_e32 v136, 0xffffc030, v68
	v_lshrrev_b32_e32 v16, 2, v136
	v_add_u32_e32 v22, 2, v16
	v_lshlrev_b64 v[16:17], 12, v[136:137]
	v_mov_b32_e32 v21, v137
	v_lshl_add_u64 v[18:19], s[10:11], 0, v[16:17]
	v_lshlrev_b64 v[16:17], 12, v[20:21]
	s_andn2_saveexec_b64 s[6:7], s[6:7]
	v_ashrrev_i32_e32 v21, 31, v20
	v_lshlrev_b64 v[16:17], 12, v[20:21]
	v_lshl_add_u64 v[18:19], s[8:9], 0, v[16:17]
	v_mov_b32_e32 v22, s27
	s_or_b64 exec, exec, s[6:7]
	v_mov_b64_e32 v[20:21], s[38:39]
	v_mad_i64_i32 v[20:21], s[6:7], v22, s51, v[20:21]
	v_lshl_add_u64 v[26:27], v[20:21], 0, v[146:147]
	v_add_co_u32_e32 v22, vcc, 0x2102000, v26
	v_lshl_add_u64 v[28:29], v[18:19], 0, v[146:147]
	s_nop 0
	v_addc_co_u32_e32 v23, vcc, 0, v27, vcc
	global_load_dwordx4 v[18:21], v[28:29], off nt
	s_nop 0
	global_load_dwordx4 v[22:25], v[22:23], off
	v_lshl_add_u64 v[30:31], v[148:149], 0, v[16:17]
	v_lshl_add_u64 v[26:27], v[26:27], 0, s[24:25]
	s_andn2_b64 vcc, exec, s[4:5]
	s_mov_b64 s[4:5], -1
	s_waitcnt vmcnt(0)
	v_pk_fma_f32 v[14:15], v[14:15], v[24:25], v[20:21]
	v_pk_fma_f32 v[12:13], v[12:13], v[22:23], v[18:19]
	global_store_dwordx4 v[30:31], v[12:15], off
	global_load_dwordx4 v[12:15], v[26:27], off offset:16
	s_nop 0
	global_load_dwordx4 v[16:19], v[28:29], off offset:16 nt
	s_waitcnt vmcnt(0)
	v_pk_fma_f32 v[10:11], v[10:11], v[14:15], v[18:19]
	v_pk_fma_f32 v[8:9], v[8:9], v[12:13], v[16:17]
	global_store_dwordx4 v[30:31], v[8:11], off offset:16
	global_load_dwordx4 v[8:11], v[26:27], off offset:512
	s_nop 0
	global_load_dwordx4 v[12:15], v[28:29], off offset:512 nt
	s_waitcnt vmcnt(0)
	v_pk_fma_f32 v[6:7], v[6:7], v[10:11], v[14:15]
	v_pk_fma_f32 v[4:5], v[4:5], v[8:9], v[12:13]
	global_store_dwordx4 v[30:31], v[4:7], off offset:512
	global_load_dwordx4 v[4:7], v[26:27], off offset:528
	s_nop 0
	global_load_dwordx4 v[8:11], v[28:29], off offset:528 nt
	s_waitcnt vmcnt(0)
	v_pk_fma_f32 v[2:3], v[2:3], v[6:7], v[10:11]
	v_pk_fma_f32 v[0:1], v[0:1], v[4:5], v[8:9]
	global_store_dwordx4 v[30:31], v[0:3], off offset:528
	s_cbranch_vccnz .LBB0_1668
	s_andn2_b64 vcc, exec, s[16:17]
	s_cbranch_vccnz .LBB0_1667
	s_barrier
	s_branch .LBB0_1667
